# combined build with chunk-MLP split 1/5 (P3) 0/4 (P5)
# baseline (speedup 1.0000x reference)
.LBB0_682:
	s_mul_i32 s5, s2, 1
	s_add_i32 s5, s5, 0
	s_mov_b32 s3, 1
	s_cmpk_lt_i32 s2, 0x80
	s_cbranch_scc1 .Lcma_hd
	s_mul_i32 s5, s2, 5
	s_add_i32 s5, s5, -512
	s_mov_b32 s3, 5

.LBB0_947:
	s_or_b64 exec, exec, s[0:1]
	s_waitcnt vmcnt(1)
	v_mov_b32_e32 v1, v195
	s_cmpk_lt_i32 s2, 0x200
	s_waitcnt lgkmcnt(0)
	s_barrier
	s_nop 0
	s_nop 0
	s_nop 0
	s_nop 0
	s_nop 0
	s_nop 0
	s_nop 0
	s_nop 0
	s_nop 0
	s_nop 0
	s_nop 0
	s_nop 0
	s_nop 0
	s_nop 0
	s_nop 0
	s_cselect_b64 s[4:5], -1, 0
	s_cmpk_gt_i32 s2, 0x1ff
	v_readfirstlane_b32 s3, v1
	s_cbranch_scc1 .LBB0_950
	s_and_b32 s8, s2, 7
	s_bfe_u32 s1, s2, 0x50003
	s_cmpk_gt_i32 s2, 0xff
	s_cbranch_scc0 .LBB0_951
	s_lshl_b32 s0, s8, 1
	s_bfe_u32 s6, s2, 0x10003
	s_or_b32 s0, s0, s6
	s_lshr_b32 s73, s1, 3
	s_or_b32 s0, s0, 64
	s_bfe_u32 s38, s2, 0x20004
	s_cmp_gt_u32 s1, 15
	s_cselect_b32 s6, 0x2800000, 0
	s_lshl_b32 s12, s73, 10
	s_mov_b32 s11, 0
	s_and_b32 s7, s12, 0x400
	s_or_b32 s10, s6, s7
	s_mov_b32 s13, s11
	s_mov_b32 s74, 8
	s_cbranch_execz .LBB0_952
	s_branch .LBB0_953
